# one static s_setprio 1 for waves 4-7 (younger half) across the hand-written cross-attention and dilated-attention phases
# speedup vs baseline: 1.0104x; 1.0104x over previous
; #define LAS __attribute__((address_space(3)))
; DI void dil_attn_phase(LAS unsigned char* L, const bf16* Z, const float* cosT, const float* sinT, bf16* OG, float* LSE, int G, int bid, int tid, unsigned long long& tsec) {
;     ...
;     const int wid = __builtin_amdgcn_readfirstlane(tid >> 6), lane = tid & 63, fr = lane & 15, fq = lane >> 4;
;     LAS unsigned char* KL = L; LAS unsigned char* VL = L + KL_BYTES;
;     u32x4 kreg[8], vreg[8];
;     ...
;     if (bid < 1536) DIL_LOAD(bid);
;     for (int unit = bid; unit < 1536; unit += G) {
;         const int j = unit & 31, h = (unit >> 5) & 3, gb = unit >> 7, g = gb % 3, b = gb / 3;
;         const int dsh = 2 * g, Lseg = T >> dsh;
;         const int p0 = 128 * j, r = p0 / Lseg, u0 = p0 & (Lseg - 1);
;         const int tokbase = b * T + r;
;         const int colq = g * 512 + h * 128;
;         asm volatile("" : "+v"(kreg[0]), "+v"(kreg[1]), "+v"(kreg[2]), "+v"(kreg[3]), "+v"(kreg[4]), "+v"(kreg[5]), "+v"(kreg[6]), "+v"(kreg[7]));
;         asm volatile("" : "+v"(vreg[0]), "+v"(vreg[1]), "+v"(vreg[2]), "+v"(vreg[3]), "+v"(vreg[4]), "+v"(vreg[5]), "+v"(vreg[6]), "+v"(vreg[7]));
;         const int qi = 16 * wid + fr; const size_t tq = (size_t)(tokbase + ((u0 + qi) << dsh));
;         bf16x8 qf[4];
; #pragma unroll
;         for (int k4 = 0; k4 < 4; ++k4) qf[k4] = *(const bf16x8*)(Z + tq * NATT + colq + 32 * k4 + 8 * fq);
.LBB0_385:
	s_cmpk_gt_i32 s28, 0x5ff
	v_readfirstlane_b32 s2, v71
	s_cbranch_scc1 .LBB0_391
	s_lshr_b32 s3, s2, 6
	s_lshl_b32 s40, s3, 13
	s_cmp_ge_u32 s3, 4
	s_cbranch_scc0 .Lda_prio
	s_setprio 1
.Lda_prio:
	s_mov_b32 s48, 0x3f317217
	s_add_u32 s34, s78, 0x6400000
	s_addc_u32 s35, s79, 0
	s_add_u32 s36, s78, 0xf400000
	s_addc_u32 s37, s79, 0
	s_add_u32 s38, s78, 0x14600000
	s_addc_u32 s39, s79, 0
	v_and_b32_e32 v186, 63, v71
	v_and_b32_e32 v187, 15, v186
	v_lshrrev_b32_e32 v188, 4, v186
	v_lshl_add_u32 v189, s3, 4, v187
	s_and_b32 s4, s3, 6
	v_lshlrev_b32_e32 v190, 2, v188
	v_lshl_add_u32 v190, s4, 4, v190
	v_xor_b32_e32 v191, 16, v186
	v_lshlrev_b32_e32 v191, 2, v191
	v_xor_b32_e32 v192, 32, v186
	v_lshlrev_b32_e32 v192, 2, v192
	v_lshl_add_u32 v193, s3, 5, v188
	v_mov_b32_e32 v217, 0xff800000
	v_add_u32_e32 v218, 0, v188
	v_xor_b32_e32 v218, v218, v187
	v_lshlrev_b32_e32 v198, 4, v218
	v_lshlrev_b32_e32 v218, 2, v188
	v_or_b32_e32 v218, 0, v218
	v_xor_b32_e32 v218, v218, v187
	v_lshlrev_b32_e32 v206, 4, v218
	v_add_u32_e32 v218, 4, v188
	v_xor_b32_e32 v218, v218, v187
	v_lshlrev_b32_e32 v199, 4, v218
	v_lshlrev_b32_e32 v218, 2, v188
	v_or_b32_e32 v218, 1, v218
	v_xor_b32_e32 v218, v218, v187
	v_lshlrev_b32_e32 v207, 4, v218
	v_add_u32_e32 v218, 8, v188
	v_xor_b32_e32 v218, v218, v187
	v_lshlrev_b32_e32 v200, 4, v218
	v_lshlrev_b32_e32 v218, 2, v188
	v_or_b32_e32 v218, 2, v218
	v_xor_b32_e32 v218, v218, v187
	v_lshlrev_b32_e32 v208, 4, v218
	v_add_u32_e32 v218, 12, v188
	v_xor_b32_e32 v218, v218, v187
	v_lshlrev_b32_e32 v201, 4, v218
	v_lshlrev_b32_e32 v218, 2, v188
	v_or_b32_e32 v218, 3, v218
	v_xor_b32_e32 v218, v218, v187
	v_lshlrev_b32_e32 v209, 4, v218
	v_lshl_add_u32 v219, s4, 4, v187
	v_lshlrev_b32_e32 v219, 8, v219
	v_add_u32_e32 v218, 0, v188
	v_xor_b32_e32 v218, v218, v187
	v_lshl_add_u32 v174, v218, 4, v219
	v_add_u32_e32 v218, 4, v188
	v_xor_b32_e32 v218, v218, v187
	v_lshl_add_u32 v175, v218, 4, v219
	v_add_u32_e32 v218, 8, v188
	v_xor_b32_e32 v218, v218, v187
	v_lshl_add_u32 v176, v218, 4, v219
	v_add_u32_e32 v218, 12, v188
	v_xor_b32_e32 v218, v218, v187
	v_lshl_add_u32 v177, v218, 4, v219
	v_lshrrev_b32_e32 v220, 2, v187
	v_lshl_add_u32 v219, v188, 2, v220
	v_lshl_add_u32 v219, s4, 4, v219
	v_lshlrev_b32_e32 v219, 8, v219
	v_lshl_or_b32 v221, v220, 2, v188
	v_bfe_u32 v222, v187, 1, 1
	v_and_b32_e32 v223, 1, v187
	v_lshl_add_u32 v219, v223, 3, v219
	v_add_u32_e32 v219, 0x10000, v219
	v_or_b32_e32 v218, 0, v222
	v_xor_b32_e32 v218, v218, v221
	v_lshl_add_u32 v178, v218, 4, v219
	v_or_b32_e32 v218, 2, v222
	v_xor_b32_e32 v218, v218, v221
	v_lshl_add_u32 v179, v218, 4, v219
	v_or_b32_e32 v218, 4, v222
	v_xor_b32_e32 v218, v218, v221
	v_lshl_add_u32 v180, v218, 4, v219
	v_or_b32_e32 v218, 6, v222
	v_xor_b32_e32 v218, v218, v221
	v_lshl_add_u32 v181, v218, 4, v219
	v_or_b32_e32 v218, 8, v222
	v_xor_b32_e32 v218, v218, v221
	v_lshl_add_u32 v182, v218, 4, v219
	v_or_b32_e32 v218, 10, v222
	v_xor_b32_e32 v218, v218, v221
	v_lshl_add_u32 v183, v218, 4, v219
	v_or_b32_e32 v218, 12, v222
	v_xor_b32_e32 v218, v218, v221
	v_lshl_add_u32 v184, v218, 4, v219
	v_or_b32_e32 v218, 14, v222
	v_xor_b32_e32 v218, v218, v221
	v_lshl_add_u32 v185, v218, 4, v219
	s_mov_b32 s5, s28
	s_and_b32 s41, s5, 31
	s_bfe_u32 s42, s5, 0x20005
	s_lshr_b32 s43, s5, 7
	s_mul_i32 s23, s43, 11
	s_lshr_b32 s23, s23, 5
	s_mul_i32 s25, s23, 3
	s_sub_u32 s25, s43, s25
	s_lshl_b32 s50, s25, 1
	s_lshl_b32 s26, s41, 7
	s_sub_u32 s27, 12, s50
	s_lshr_b32 s27, s26, s27
	s_lshr_b32 s51, 0xfff, s50
	s_and_b32 s51, s26, s51
	s_lshl_b32 s23, s23, 12
	s_add_u32 s23, s23, s27
	s_lshl_b32 s26, s25, 10
	s_lshl_b32 s27, s42, 8
	s_add_u32 s26, s26, s27
	s_mul_i32 s27, s23, 0x2400
	s_add_u32 s27, s27, s26
	s_add_u32 s52, s34, s27
	s_addc_u32 s53, s35, 0
	s_mov_b32 s18, s50
	s_mov_b32 s19, s51
	s_mul_i32 s27, s23, 0xc00
	s_add_u32 s27, s27, s26
	s_add_u32 s14, s36, s27
	s_addc_u32 s15, s37, 0
	s_mul_i32 s27, s23, 48
	s_lshl_b32 s26, s25, 4
	s_lshl_b32 s23, s42, 2
	s_add_u32 s26, s26, s23
	s_add_u32 s27, s27, s26
	s_add_u32 s16, s38, s27
	s_addc_u32 s17, s39, 0
	v_add_u32_e32 v218, s19, v189
	v_lshlrev_b32_e32 v218, s18, v218
	v_mul_u32_u24_e32 v219, 3, v218
	v_lshlrev_b32_e32 v219, 10, v219
	v_lshl_add_u32 v213, v188, 3, v219
	v_mul_u32_u24_e32 v214, 48, v218
	s_cmp_eq_u32 s19, 0
	s_cselect_b32 s23, 0x80, 0
	v_max_u32_e32 v219, s23, v189
	v_sub_u32_e32 v215, v190, v219
	v_sub_u32_e32 v216, v189, v219
	v_add_u32_e32 v216, 0x80, v216
	v_add_u32_e32 v218, s51, v189
	v_lshlrev_b32_e32 v218, s50, v218
	v_mul_u32_u24_e32 v218, 9, v218
	v_lshlrev_b32_e32 v218, 10, v218
	v_lshl_add_u32 v212, v188, 4, v218
	s_add_u32 s44, s52, 3072
; DI void dil_attn_phase(LAS unsigned char* L, const bf16* Z, const float* cosT, const float* sinT, bf16* OG, float* LSE, int G, int bid, int tid, unsigned long long& tsec) {
;     ...
;     if (bid < 1536) DIL_LOAD(bid);
;     for (int unit = bid; unit < 1536; unit += G) {
;         const int j = unit & 31, h = (unit >> 5) & 3, gb = unit >> 7, g = gb % 3, b = gb / 3;
;         const int dsh = 2 * g, Lseg = T >> dsh;
;         const int p0 = 128 * j, r = p0 / Lseg, u0 = p0 & (Lseg - 1);
;         const int tokbase = b * T + r;
;         const int colq = g * 512 + h * 128;
;         asm volatile("" : "+v"(kreg[0]), "+v"(kreg[1]), "+v"(kreg[2]), "+v"(kreg[3]), "+v"(kreg[4]), "+v"(kreg[5]), "+v"(kreg[6]), "+v"(kreg[7]));
;         asm volatile("" : "+v"(vreg[0]), "+v"(vreg[1]), "+v"(vreg[2]), "+v"(vreg[3]), "+v"(vreg[4]), "+v"(vreg[5]), "+v"(vreg[6]), "+v"(vreg[7]));
;         const int qi = 16 * wid + fr; const size_t tq = (size_t)(tokbase + ((u0 + qi) << dsh));
;         bf16x8 qf[4];
; #pragma unroll
;         for (int k4 = 0; k4 < 4; ++k4) qf[k4] = *(const bf16x8*)(Z + tq * NATT + colq + 32 * k4 + 8 * fq);
;         __syncthreads();
	s_addc_u32 s45, s53, 0
	s_sub_u32 s23, s51, 0x80
	v_add_u32_e32 v218, 0, v193
	v_add_u32_e32 v218, s23, v218
	v_max_i32_e32 v218, 0, v218
	v_lshlrev_b32_e32 v218, s50, v218
	v_mul_u32_u24_e32 v218, 9, v218
	v_lshl_add_u32 v218, v218, 10, v198
	s_add_u32 m0, s40, 0
	s_nop 0
	global_load_lds_dwordx4 v218, s[44:45]
	v_add_u32_e32 v218, 4, v193
	v_add_u32_e32 v218, s23, v218
	v_max_i32_e32 v218, 0, v218
	v_lshlrev_b32_e32 v218, s50, v218
	v_mul_u32_u24_e32 v218, 9, v218
	v_lshl_add_u32 v218, v218, 10, v199
	s_add_u32 m0, s40, 1024
	s_nop 0
	global_load_lds_dwordx4 v218, s[44:45]
	v_add_u32_e32 v218, 8, v193
	v_add_u32_e32 v218, s23, v218
	v_max_i32_e32 v218, 0, v218
	v_lshlrev_b32_e32 v218, s50, v218
	v_mul_u32_u24_e32 v218, 9, v218
	v_lshl_add_u32 v218, v218, 10, v200
	s_add_u32 m0, s40, 2048
	s_nop 0
	global_load_lds_dwordx4 v218, s[44:45]
	v_add_u32_e32 v218, 12, v193
	v_add_u32_e32 v218, s23, v218
	v_max_i32_e32 v218, 0, v218
	v_lshlrev_b32_e32 v218, s50, v218
	v_mul_u32_u24_e32 v218, 9, v218
	v_lshl_add_u32 v218, v218, 10, v201
	s_add_u32 m0, s40, 3072
	s_nop 0
	global_load_lds_dwordx4 v218, s[44:45]
	v_add_u32_e32 v218, 16, v193
	v_add_u32_e32 v218, s23, v218
	v_max_i32_e32 v218, 0, v218
	v_lshlrev_b32_e32 v218, s50, v218
	v_mul_u32_u24_e32 v218, 9, v218
	v_lshl_add_u32 v218, v218, 10, v198
	s_add_u32 m0, s40, 4096
	s_nop 0
	global_load_lds_dwordx4 v218, s[44:45]
	v_add_u32_e32 v218, 20, v193
	v_add_u32_e32 v218, s23, v218
	v_max_i32_e32 v218, 0, v218
	v_lshlrev_b32_e32 v218, s50, v218
	v_mul_u32_u24_e32 v218, 9, v218
	v_lshl_add_u32 v218, v218, 10, v199
	s_add_u32 m0, s40, 5120
	s_nop 0
	global_load_lds_dwordx4 v218, s[44:45]
	v_add_u32_e32 v218, 24, v193
	v_add_u32_e32 v218, s23, v218
	v_max_i32_e32 v218, 0, v218
	v_lshlrev_b32_e32 v218, s50, v218
	v_mul_u32_u24_e32 v218, 9, v218
	v_lshl_add_u32 v218, v218, 10, v200
	s_add_u32 m0, s40, 6144
	s_nop 0
	global_load_lds_dwordx4 v218, s[44:45]
	v_add_u32_e32 v218, 28, v193
	v_add_u32_e32 v218, s23, v218
	v_max_i32_e32 v218, 0, v218
	v_lshlrev_b32_e32 v218, s50, v218
	v_mul_u32_u24_e32 v218, 9, v218
	v_lshl_add_u32 v218, v218, 10, v201
	s_add_u32 m0, s40, 7168
	s_nop 0
	global_load_lds_dwordx4 v218, s[44:45]
	global_load_dwordx4 v[42:45], v212, s[52:53]
	global_load_dwordx4 v[46:49], v212, s[52:53] offset:64
	global_load_dwordx4 v[50:53], v212, s[52:53] offset:128
	global_load_dwordx4 v[54:57], v212, s[52:53] offset:192
	s_add_u32 s44, s52, 6144
	s_addc_u32 s45, s53, 0
	s_sub_u32 s23, s51, 0x80
	v_add_u32_e32 v218, 0, v193
	v_add_u32_e32 v218, s23, v218
	v_max_i32_e32 v218, 0, v218
	v_lshlrev_b32_e32 v218, s50, v218
	v_mul_u32_u24_e32 v218, 9, v218
	v_lshl_add_u32 v218, v218, 10, v206
	s_add_u32 m0, s40, 65536
	s_nop 0
	global_load_lds_dwordx4 v218, s[44:45]
	v_add_u32_e32 v218, 4, v193
	v_add_u32_e32 v218, s23, v218
	v_max_i32_e32 v218, 0, v218
	v_lshlrev_b32_e32 v218, s50, v218
	v_mul_u32_u24_e32 v218, 9, v218
	v_lshl_add_u32 v218, v218, 10, v207
	s_add_u32 m0, s40, 66560
	s_nop 0
	global_load_lds_dwordx4 v218, s[44:45]
	v_add_u32_e32 v218, 8, v193
	v_add_u32_e32 v218, s23, v218
	v_max_i32_e32 v218, 0, v218
	v_lshlrev_b32_e32 v218, s50, v218
	v_mul_u32_u24_e32 v218, 9, v218
	v_lshl_add_u32 v218, v218, 10, v208
	s_add_u32 m0, s40, 67584
	s_nop 0
	global_load_lds_dwordx4 v218, s[44:45]
	v_add_u32_e32 v218, 12, v193
	v_add_u32_e32 v218, s23, v218
	v_max_i32_e32 v218, 0, v218
	v_lshlrev_b32_e32 v218, s50, v218
	v_mul_u32_u24_e32 v218, 9, v218
	v_lshl_add_u32 v218, v218, 10, v209
	s_add_u32 m0, s40, 68608
	s_nop 0
	global_load_lds_dwordx4 v218, s[44:45]
	v_add_u32_e32 v218, 16, v193
	v_add_u32_e32 v218, s23, v218
	v_max_i32_e32 v218, 0, v218
	v_lshlrev_b32_e32 v218, s50, v218
	v_mul_u32_u24_e32 v218, 9, v218
	v_lshl_add_u32 v218, v218, 10, v206
	s_add_u32 m0, s40, 69632
	s_nop 0
	global_load_lds_dwordx4 v218, s[44:45]
	v_add_u32_e32 v218, 20, v193
	v_add_u32_e32 v218, s23, v218
	v_max_i32_e32 v218, 0, v218
	v_lshlrev_b32_e32 v218, s50, v218
	v_mul_u32_u24_e32 v218, 9, v218
	v_lshl_add_u32 v218, v218, 10, v207
	s_add_u32 m0, s40, 70656
	s_nop 0
	global_load_lds_dwordx4 v218, s[44:45]
	v_add_u32_e32 v218, 24, v193
	v_add_u32_e32 v218, s23, v218
	v_max_i32_e32 v218, 0, v218
	v_lshlrev_b32_e32 v218, s50, v218
	v_mul_u32_u24_e32 v218, 9, v218
	v_lshl_add_u32 v218, v218, 10, v208
	s_add_u32 m0, s40, 71680
	s_nop 0
	global_load_lds_dwordx4 v218, s[44:45]
	v_add_u32_e32 v218, 28, v193
	v_add_u32_e32 v218, s23, v218
	v_max_i32_e32 v218, 0, v218
	v_lshlrev_b32_e32 v218, s50, v218
	v_mul_u32_u24_e32 v218, 9, v218
	v_lshl_add_u32 v218, v218, 10, v209
	s_add_u32 m0, s40, 72704
	s_nop 0
	global_load_lds_dwordx4 v218, s[44:45]
	s_waitcnt vmcnt(8)
	s_barrier

; DI void dil_attn_phase(LAS unsigned char* L, const bf16* Z, const float* cosT, const float* sinT, bf16* OG, float* LSE, int G, int bid, int tid, unsigned long long& tsec) {
;     ...
;     }
;     ...
; }
.Lda_done:
	s_setprio 0

; #define LAS __attribute__((address_space(3)))
; #define XK_LOAD(R, b_, h_, hh_) do { _Pragma("unroll") for (int i = 0; i < 8; ++i) { const int p = tid + 512 * i, m = p >> 4, cb = p & 15; R[i] = *(const u32x4*)(memK + (size_t)((b_) * NMEM + m) * D + (h_) * 256 + 128 * (hh_) + 8 * cb); } } while (0)
; #define XV_LOAD(R, b_, h_, hh_) do { _Pragma("unroll") for (int i = 0; i < 8; ++i) { const int p = tid + 512 * i, dhr = p >> 5, c = p & 31; R[i] = *(const u32x4*)(memVT + (size_t)((h_) * 256 + 128 * (hh_) + dhr) * MROWS + (b_) * NMEM + 8 * c); } } while (0)
; DI void xattn_phase(LAS unsigned char* L, const bf16* Qx, const bf16* memK, const bf16* memVT, bf16* Ox, int G, int bid, int tid, unsigned long long& tsec) {
;     unsigned long long tl_ = PROBE_DSEC ? __builtin_amdgcn_s_memrealtime() : 0;
;     const int wid = __builtin_amdgcn_readfirstlane(tid >> 6), lane = tid & 63, fr = lane & 15, fq = lane >> 4;
;     LAS unsigned char* KL = L; LAS unsigned char* VL = L + KL_BYTES;
;     u32x4 ra[8], rb[8];
;     if (bid < 512) { const int h0 = (bid >> 5) & 3, b0 = bid >> 7; XK_LOAD(ra, b0, h0, 0); XV_LOAD(rb, b0, h0, 0); }
;     for (int unit = bid; unit < 512; unit += G) {
;         const int j = unit & 31, h = (unit >> 5) & 3, b = unit >> 7;
;         const int nun = unit + G < 512 ? unit + G : unit, hn = (nun >> 5) & 3, bn = nun >> 7;
.LBB0_1099:
	s_cmpk_gt_i32 s4, 0x1ff
	v_readfirstlane_b32 s5, v67
	s_cbranch_scc1 .LBB0_1102
	v_readlane_b32 s2, v254, 29
	v_readlane_b32 s3, v254, 30
	s_and_b64 s[2:3], s[2:3], exec
	s_brev_b32 s2, 40
	s_mov_b32 s3, 0x14200000
	s_cselect_b32 s2, s2, 0x14c00000
	s_cselect_b32 s3, s3, 0x14e00000
	s_add_u32 s6, s78, s0
	s_addc_u32 s7, s79, s1
	s_add_u32 s0, s6, 0x6400000
	s_addc_u32 s1, s7, 0
	s_add_u32 s36, s6, s2
	s_addc_u32 s37, s7, 0
	s_add_u32 s2, s6, s3
	s_addc_u32 s3, s7, 0
	s_add_u32 s38, s6, 0x8400000
	s_addc_u32 s39, s7, 0
	s_lshr_b32 s16, s5, 6
	s_lshl_b32 s49, s16, 13
	s_cmp_ge_u32 s16, 4
	s_cbranch_scc0 .Lxa_prio
	s_setprio 1
; #define XK_LOAD(R, b_, h_, hh_) do { _Pragma("unroll") for (int i = 0; i < 8; ++i) { const int p = tid + 512 * i, m = p >> 4, cb = p & 15; R[i] = *(const u32x4*)(memK + (size_t)((b_) * NMEM + m) * D + (h_) * 256 + 128 * (hh_) + 8 * cb); } } while (0)
; #define XK_WRITE(R) do { _Pragma("unroll") for (int i = 0; i < 8; ++i) { const int p = tid + 512 * i, m = p >> 4, cb = p & 15; *(LAS u32x4*)(KL + m * KSTR + 16 * cb) = R[i]; } } while (0)
; #define XV_LOAD(R, b_, h_, hh_) do { _Pragma("unroll") for (int i = 0; i < 8; ++i) { const int p = tid + 512 * i, dhr = p >> 5, c = p & 31; R[i] = *(const u32x4*)(memVT + (size_t)((h_) * 256 + 128 * (hh_) + dhr) * MROWS + (b_) * NMEM + 8 * c); } } while (0)
; #define XV_WRITE(R) do { _Pragma("unroll") for (int i = 0; i < 8; ++i) { const int p = tid + 512 * i, dhr = p >> 5, c = p & 31; u32x2 lo, hi; lo.x = R[i].x; lo.y = R[i].y; hi.x = R[i].z; hi.y = R[i].w; \
;         *(LAS u32x2*)(VL + vt_off(dhr, 2 * c)) = lo; *(LAS u32x2*)(VL + vt_off(dhr, 2 * c + 1)) = hi; } } while (0)
; DI void xattn_phase(LAS unsigned char* L, const bf16* Qx, const bf16* memK, const bf16* memVT, bf16* Ox, int G, int bid, int tid, unsigned long long& tsec) {
;     ...
;     if (bid < 512) { const int h0 = (bid >> 5) & 3, b0 = bid >> 7; XK_LOAD(ra, b0, h0, 0); XV_LOAD(rb, b0, h0, 0); }
;     for (int unit = bid; unit < 512; unit += G) {
;         const int j = unit & 31, h = (unit >> 5) & 3, b = unit >> 7;
;         const int nun = unit + G < 512 ? unit + G : unit, hn = (nun >> 5) & 3, bn = nun >> 7;
;         asm volatile("" : "+v"(ra[0]), "+v"(ra[1]), "+v"(ra[2]), "+v"(ra[3]), "+v"(ra[4]), "+v"(ra[5]), "+v"(ra[6]), "+v"(ra[7]));
;         asm volatile("" : "+v"(rb[0]), "+v"(rb[1]), "+v"(rb[2]), "+v"(rb[3]), "+v"(rb[4]), "+v"(rb[5]), "+v"(rb[6]), "+v"(rb[7]));
;         const int tok0 = b * T + 128 * j; const size_t tq = (size_t)(tok0 + 16 * wid + fr);
;         f32x4 s[16];
; #pragma unroll
;         for (int kt = 0; kt < 16; ++kt) s[kt] = (f32x4){0.f, 0.f, 0.f, 0.f};
; #pragma unroll
;         for (int hh = 0; hh < 2; ++hh) {
;             __syncthreads();
;             XK_WRITE(ra);
;             if (hh == 0) { XV_WRITE(rb); XK_LOAD(ra, b, h, 1); XV_LOAD(rb, b, h, 1); }
;             else XK_LOAD(ra, bn, hn, 0);
;             __syncthreads();
.Lxa_prio:
	s_mov_b32 s48, 0x3d800000
	v_and_b32_e32 v236, 63, v67
	v_and_b32_e32 v237, 15, v236
	v_lshrrev_b32_e32 v248, 4, v236
	v_xor_b32_e32 v234, 16, v236
	v_lshlrev_b32_e32 v234, 2, v234
	v_xor_b32_e32 v235, 32, v236
	v_lshlrev_b32_e32 v235, 2, v235
	v_add_u32_e32 v249, 0, v248
	v_xor_b32_e32 v198, v237, v249
	v_lshl_add_u32 v249, s16, 5, v249
	v_lshlrev_b32_e32 v249, 11, v249
	v_lshl_add_u32 v198, v198, 4, v249
	v_add_u32_e32 v249, 4, v248
	v_xor_b32_e32 v199, v237, v249
	v_lshl_add_u32 v249, s16, 5, v249
	v_lshlrev_b32_e32 v249, 11, v249
	v_lshl_add_u32 v199, v199, 4, v249
	v_add_u32_e32 v249, 8, v248
	v_xor_b32_e32 v200, v237, v249
	v_lshl_add_u32 v249, s16, 5, v249
	v_lshlrev_b32_e32 v249, 11, v249
	v_lshl_add_u32 v200, v200, 4, v249
	v_add_u32_e32 v249, 12, v248
	v_xor_b32_e32 v201, v237, v249
	v_lshl_add_u32 v249, s16, 5, v249
	v_lshlrev_b32_e32 v249, 11, v249
	v_lshl_add_u32 v201, v201, 4, v249
	v_add_u32_e32 v249, 0, v248
	v_xor_b32_e32 v249, v249, v237
	v_lshlrev_b32_e32 v249, 4, v249
	v_lshl_add_u32 v206, v237, 8, v249
	v_add_u32_e32 v212, 0x10000, v206
	v_add_u32_e32 v249, 4, v248
	v_xor_b32_e32 v249, v249, v237
	v_lshlrev_b32_e32 v249, 4, v249
	v_lshl_add_u32 v207, v237, 8, v249
	v_add_u32_e32 v213, 0x10000, v207
	v_add_u32_e32 v249, 8, v248
	v_xor_b32_e32 v249, v249, v237
	v_lshlrev_b32_e32 v249, 4, v249
	v_lshl_add_u32 v208, v237, 8, v249
	v_add_u32_e32 v214, 0x10000, v208
	v_add_u32_e32 v249, 12, v248
	v_xor_b32_e32 v249, v249, v237
	v_lshlrev_b32_e32 v249, 4, v249
	v_lshl_add_u32 v209, v237, 8, v249
	v_add_u32_e32 v215, 0x10000, v209
	v_lshrrev_b32_e32 v0, 1, v248
	v_add_u32_e32 v249, 0, v0
	v_xor_b32_e32 v249, v249, v237
	v_lshlrev_b32_e32 v249, 4, v249
	v_lshl_add_u32 v216, v237, 9, v249
	v_add_u32_e32 v249, 2, v0
	v_xor_b32_e32 v249, v249, v237
	v_lshlrev_b32_e32 v249, 4, v249
	v_lshl_add_u32 v217, v237, 9, v249
	v_add_u32_e32 v249, 4, v0
	v_xor_b32_e32 v249, v249, v237
	v_lshlrev_b32_e32 v249, 4, v249
	v_lshl_add_u32 v218, v237, 9, v249
	v_add_u32_e32 v249, 6, v0
	v_xor_b32_e32 v249, v249, v237
	v_lshlrev_b32_e32 v249, 4, v249
	v_lshl_add_u32 v219, v237, 9, v249
	v_add_u32_e32 v249, 8, v0
	v_xor_b32_e32 v249, v249, v237
	v_lshlrev_b32_e32 v249, 4, v249
	v_lshl_add_u32 v220, v237, 9, v249
	v_add_u32_e32 v249, 10, v0
	v_xor_b32_e32 v249, v249, v237
	v_lshlrev_b32_e32 v249, 4, v249
	v_lshl_add_u32 v221, v237, 9, v249
	v_add_u32_e32 v249, 12, v0
	v_xor_b32_e32 v249, v249, v237
	v_lshlrev_b32_e32 v249, 4, v249
	v_lshl_add_u32 v222, v237, 9, v249
	v_add_u32_e32 v249, 14, v0
	v_xor_b32_e32 v249, v249, v237
	v_lshlrev_b32_e32 v249, 4, v249
	v_lshl_add_u32 v223, v237, 9, v249
	v_and_b32_e32 v249, 1, v248
	v_lshlrev_b32_e32 v249, 3, v249
	v_add_u32_e32 v216, v216, v249
	v_add_u32_e32 v224, 0x10000, v216
	v_add_u32_e32 v217, v217, v249
	v_add_u32_e32 v225, 0x10000, v217
	v_add_u32_e32 v218, v218, v249
	v_add_u32_e32 v226, 0x10000, v218
	v_add_u32_e32 v219, v219, v249
	v_add_u32_e32 v227, 0x10000, v219
	v_add_u32_e32 v220, v220, v249
	v_add_u32_e32 v228, 0x10000, v220
	v_add_u32_e32 v221, v221, v249
	v_add_u32_e32 v229, 0x10000, v221
	v_add_u32_e32 v222, v222, v249
	v_add_u32_e32 v230, 0x10000, v222
	v_add_u32_e32 v223, v223, v249
	v_add_u32_e32 v231, 0x10000, v223
	v_lshl_add_u32 v249, s16, 4, v237
	v_lshlrev_b32_e32 v249, 11, v249
	v_lshl_add_u32 v232, v248, 4, v249
	v_lshl_add_u32 v233, v248, 3, v249
	v_readlane_b32 s44, v252, 0
	s_nop 3
	s_and_b32 s45, s44, 7
	s_lshr_b32 s46, s44, 3
	s_and_b32 s47, s45, 1
	s_lshl_b32 s47, s47, 4
	s_and_b32 s17, s46, 15
	s_or_b32 s17, s17, s47
	s_lshr_b32 s47, s46, 4
	s_lshl_b32 s47, s47, 6
	s_or_b32 s17, s17, s47
	s_lshr_b32 s47, s45, 1
	s_lshl_b32 s47, s47, 7
	s_or_b32 s17, s17, s47
	s_and_b32 s44, s17, 31
	s_bfe_u32 s45, s17, 0x20005
	s_lshr_b32 s46, s17, 7
	s_lshl_b32 s47, s46, 12
	s_lshl_b32 s44, s44, 7
	s_add_u32 s47, s47, s44
	s_lshl_b32 s47, s47, 11
	s_lshl_b32 s44, s45, 9
	s_add_u32 s47, s47, s44
	s_add_u32 s20, s0, s47
	s_addc_u32 s21, s1, 0
	s_add_u32 s22, s38, s47
	s_addc_u32 s23, s39, 0
	s_lshl_b32 s47, s46, 19
	s_add_u32 s47, s47, s44
	s_add_u32 s24, s36, s47
	s_addc_u32 s25, s37, 0
	s_lshl_b32 s47, s45, 19
	s_lshl_b32 s44, s46, 9
	s_add_u32 s47, s47, s44
	s_add_u32 s42, s2, s47
	s_addc_u32 s43, s3, 0
	s_add_u32 s44, s24, 0
	s_addc_u32 s45, s25, 0
	s_add_u32 s46, s44, 0x8000
	s_addc_u32 s47, s45, 0
	s_add_u32 m0, s49, 0
	s_nop 0
	global_load_lds_dwordx4 v198, s[44:45]
	s_add_u32 m0, s49, 1024
	s_nop 0
	global_load_lds_dwordx4 v199, s[44:45]
	s_add_u32 m0, s49, 2048
	s_nop 0
	global_load_lds_dwordx4 v200, s[44:45]
	s_add_u32 m0, s49, 3072
	s_nop 0
	global_load_lds_dwordx4 v201, s[44:45]
	s_add_u32 m0, s49, 4096
	s_nop 0
	global_load_lds_dwordx4 v198, s[46:47]
	s_add_u32 m0, s49, 5120
	s_nop 0
	global_load_lds_dwordx4 v199, s[46:47]
	s_add_u32 m0, s49, 6144
	s_nop 0
	global_load_lds_dwordx4 v200, s[46:47]
	s_add_u32 m0, s49, 7168
	s_nop 0
	global_load_lds_dwordx4 v201, s[46:47]
	global_load_dwordx4 v[66:69], v232, s[20:21]
	global_load_dwordx4 v[70:73], v232, s[20:21] offset:64
	global_load_dwordx4 v[74:77], v232, s[20:21] offset:128
	global_load_dwordx4 v[78:81], v232, s[20:21] offset:192
	global_load_dwordx4 v[82:85], v232, s[20:21] offset:256
	global_load_dwordx4 v[86:89], v232, s[20:21] offset:320
	global_load_dwordx4 v[90:93], v232, s[20:21] offset:384
	global_load_dwordx4 v[94:97], v232, s[20:21] offset:448
	s_lshl_b32 s46, s16, 1
	s_add_u32 s46, s46, 0
	v_lshl_add_u32 v237, s46, 6, v236
	v_lshrrev_b32_e32 v248, 2, v237
	v_and_b32_e32 v237, 3, v237
	v_lshlrev_b32_e32 v237, 6, v237
	v_lshl_add_u32 v237, v248, 11, v237
	global_load_dword v249, v237, s[24:25] offset:256
	s_lshl_b32 s46, s16, 1
	s_add_u32 s46, s46, 1
	v_lshl_add_u32 v237, s46, 6, v236
	v_lshrrev_b32_e32 v248, 2, v237
	v_and_b32_e32 v237, 3, v237
	v_lshlrev_b32_e32 v237, 6, v237
	v_lshl_add_u32 v237, v248, 11, v237
	global_load_dword v249, v237, s[24:25] offset:256
	s_lshl_b32 s46, s16, 2
	s_add_u32 s46, s46, 0
	v_lshl_add_u32 v237, s46, 6, v236
	v_lshrrev_b32_e32 v248, 3, v237
	v_and_b32_e32 v237, 7, v237
	v_lshlrev_b32_e32 v237, 6, v237
	v_lshl_add_u32 v237, v248, 11, v237
	global_load_dword v249, v237, s[42:43]
	s_lshl_b32 s46, s16, 2
	s_add_u32 s46, s46, 1
	v_lshl_add_u32 v237, s46, 6, v236
	v_lshrrev_b32_e32 v248, 3, v237
	v_and_b32_e32 v237, 7, v237
	v_lshlrev_b32_e32 v237, 6, v237
	v_lshl_add_u32 v237, v248, 11, v237
	global_load_dword v249, v237, s[42:43]
	s_lshl_b32 s46, s16, 2
	s_add_u32 s46, s46, 2
	v_lshl_add_u32 v237, s46, 6, v236
	v_lshrrev_b32_e32 v248, 3, v237
	v_and_b32_e32 v237, 7, v237
	v_lshlrev_b32_e32 v237, 6, v237
	v_lshl_add_u32 v237, v248, 11, v237
	global_load_dword v249, v237, s[42:43]
	s_lshl_b32 s46, s16, 2
	s_add_u32 s46, s46, 3
	v_lshl_add_u32 v237, s46, 6, v236
	v_lshrrev_b32_e32 v248, 3, v237
	v_and_b32_e32 v237, 7, v237
	v_lshlrev_b32_e32 v237, 6, v237
	v_lshl_add_u32 v237, v248, 11, v237
	global_load_dword v249, v237, s[42:43]
	s_waitcnt vmcnt(0)
	s_barrier

; #define LAS __attribute__((address_space(3)))
; #define MFMA16(a, b, c) __builtin_amdgcn_mfma_f32_16x16x32_bf16((a), (b), (c), 0, 0, 0)
; DI void xattn_phase(LAS unsigned char* L, const bf16* Qx, const bf16* memK, const bf16* memVT, bf16* Ox, int G, int bid, int tid, unsigned long long& tsec) {
;     ...
;             const unsigned x0 = (unsigned)(fq ^ (fr >> 3));
;             const LAS unsigned char* vev = L + KL_BYTES + fr * VSTR + (x0 << 3); const LAS unsigned char* vod = L + KL_BYTES + fr * VSTR + ((x0 ^ 2u) << 3);
; #pragma unroll
;             for (int pp = 0; pp < 8; ++pp)
; #pragma unroll
;                 for (int d4 = 0; d4 < 2; ++d4) { bf16x8 vf[4];
; #pragma unroll
;                     for (int dq = 0; dq < 4; ++dq) { const int dt = 4 * d4 + dq; const LAS unsigned char* vb_ = ((dt & 1) ? vod : vev) + 16 * dt * VSTR + 64 * pp;
;                         const s16x4 lo = *(const LAS s16x4*)(vb_ + (((2 * dt) & 4) << 3)), hi = *(const LAS s16x4*)(vb_ + ((((2 * dt) & 4) ^ 4) << 3)); vf[dq] = __builtin_shufflevector(lo, hi, 0, 1, 2, 3, 4, 5, 6, 7); }
; #pragma unroll
;                     for (int dq = 0; dq < 4; ++dq) o[4 * d4 + dq] = MFMA16(vf[dq], pf[pp], o[4 * d4 + dq]);
;                 }
.Lxa_last:
	ds_read_b64 v[98:99], v224 offset:0
	ds_read_b64 v[100:101], v225 offset:0
	ds_read_b64 v[102:103], v224 offset:8192
	ds_read_b64 v[104:105], v225 offset:8192
	ds_read_b64 v[106:107], v224 offset:16384
	ds_read_b64 v[108:109], v225 offset:16384
	ds_read_b64 v[110:111], v224 offset:24576
	ds_read_b64 v[112:113], v225 offset:24576
	ds_read_b64 v[114:115], v224 offset:32768
	ds_read_b64 v[116:117], v225 offset:32768
	ds_read_b64 v[118:119], v224 offset:40960
	ds_read_b64 v[120:121], v225 offset:40960
	ds_read_b64 v[122:123], v224 offset:49152
	ds_read_b64 v[124:125], v225 offset:49152
	ds_read_b64 v[126:127], v224 offset:57344
	ds_read_b64 v[128:129], v225 offset:57344
	ds_read_b64 v[130:131], v226 offset:0
	ds_read_b64 v[132:133], v227 offset:0
	ds_read_b64 v[134:135], v226 offset:8192
	ds_read_b64 v[136:137], v227 offset:8192
	ds_read_b64 v[138:139], v226 offset:16384
	ds_read_b64 v[140:141], v227 offset:16384
	ds_read_b64 v[142:143], v226 offset:24576
	ds_read_b64 v[144:145], v227 offset:24576
	ds_read_b64 v[146:147], v226 offset:32768
	ds_read_b64 v[148:149], v227 offset:32768
	ds_read_b64 v[150:151], v226 offset:40960
	ds_read_b64 v[152:153], v227 offset:40960
	ds_read_b64 v[154:155], v226 offset:49152
	ds_read_b64 v[156:157], v227 offset:49152
	ds_read_b64 v[158:159], v226 offset:57344
	ds_read_b64 v[160:161], v227 offset:57344
	s_waitcnt lgkmcnt(15)
	v_mfma_f32_16x16x32_bf16 v[34:37], v[98:101], v[162:165], 0
	ds_read_b64 v[98:99], v228 offset:0
	ds_read_b64 v[100:101], v229 offset:0
	v_mfma_f32_16x16x32_bf16 v[38:41], v[102:105], v[162:165], 0
	ds_read_b64 v[102:103], v228 offset:8192
	ds_read_b64 v[104:105], v229 offset:8192
	v_mfma_f32_16x16x32_bf16 v[42:45], v[106:109], v[162:165], 0
	ds_read_b64 v[106:107], v228 offset:16384
	ds_read_b64 v[108:109], v229 offset:16384
	v_mfma_f32_16x16x32_bf16 v[46:49], v[110:113], v[162:165], 0
	ds_read_b64 v[110:111], v228 offset:24576
	ds_read_b64 v[112:113], v229 offset:24576
	v_mfma_f32_16x16x32_bf16 v[50:53], v[114:117], v[162:165], 0
	ds_read_b64 v[114:115], v228 offset:32768
	ds_read_b64 v[116:117], v229 offset:32768
	v_mfma_f32_16x16x32_bf16 v[54:57], v[118:121], v[162:165], 0
	ds_read_b64 v[118:119], v228 offset:40960
	ds_read_b64 v[120:121], v229 offset:40960
	v_mfma_f32_16x16x32_bf16 v[58:61], v[122:125], v[162:165], 0
	ds_read_b64 v[122:123], v228 offset:49152
	ds_read_b64 v[124:125], v229 offset:49152
	v_mfma_f32_16x16x32_bf16 v[62:65], v[126:129], v[162:165], 0
	ds_read_b64 v[126:127], v228 offset:57344
	ds_read_b64 v[128:129], v229 offset:57344
	s_waitcnt lgkmcnt(15)
	v_mfma_f32_16x16x32_bf16 v[34:37], v[130:133], v[166:169], v[34:37]
	ds_read_b64 v[130:131], v230 offset:0
	ds_read_b64 v[132:133], v231 offset:0
	v_mfma_f32_16x16x32_bf16 v[38:41], v[134:137], v[166:169], v[38:41]
	ds_read_b64 v[134:135], v230 offset:8192
	ds_read_b64 v[136:137], v231 offset:8192
	v_mfma_f32_16x16x32_bf16 v[42:45], v[138:141], v[166:169], v[42:45]
	ds_read_b64 v[138:139], v230 offset:16384
	ds_read_b64 v[140:141], v231 offset:16384
	v_mfma_f32_16x16x32_bf16 v[46:49], v[142:145], v[166:169], v[46:49]
	ds_read_b64 v[142:143], v230 offset:24576
	ds_read_b64 v[144:145], v231 offset:24576
	v_mfma_f32_16x16x32_bf16 v[50:53], v[146:149], v[166:169], v[50:53]
	ds_read_b64 v[146:147], v230 offset:32768
	ds_read_b64 v[148:149], v231 offset:32768
	v_mfma_f32_16x16x32_bf16 v[54:57], v[150:153], v[166:169], v[54:57]
	ds_read_b64 v[150:151], v230 offset:40960
	ds_read_b64 v[152:153], v231 offset:40960
	v_mfma_f32_16x16x32_bf16 v[58:61], v[154:157], v[166:169], v[58:61]
	ds_read_b64 v[154:155], v230 offset:49152
	ds_read_b64 v[156:157], v231 offset:49152
	v_mfma_f32_16x16x32_bf16 v[62:65], v[158:161], v[166:169], v[62:65]
	ds_read_b64 v[158:159], v230 offset:57344
	ds_read_b64 v[160:161], v231 offset:57344
	s_waitcnt lgkmcnt(15)
	v_mfma_f32_16x16x32_bf16 v[34:37], v[98:101], v[170:173], v[34:37]
	ds_read_b64 v[98:99], v224 offset:256
	ds_read_b64 v[100:101], v225 offset:256
	v_mfma_f32_16x16x32_bf16 v[38:41], v[102:105], v[170:173], v[38:41]
	ds_read_b64 v[102:103], v224 offset:8448
	ds_read_b64 v[104:105], v225 offset:8448
	v_mfma_f32_16x16x32_bf16 v[42:45], v[106:109], v[170:173], v[42:45]
	ds_read_b64 v[106:107], v224 offset:16640
	ds_read_b64 v[108:109], v225 offset:16640
	v_mfma_f32_16x16x32_bf16 v[46:49], v[110:113], v[170:173], v[46:49]
	ds_read_b64 v[110:111], v224 offset:24832
	ds_read_b64 v[112:113], v225 offset:24832
	v_mfma_f32_16x16x32_bf16 v[50:53], v[114:117], v[170:173], v[50:53]
	ds_read_b64 v[114:115], v224 offset:33024
	ds_read_b64 v[116:117], v225 offset:33024
	v_mfma_f32_16x16x32_bf16 v[54:57], v[118:121], v[170:173], v[54:57]
	ds_read_b64 v[118:119], v224 offset:41216
	ds_read_b64 v[120:121], v225 offset:41216
	v_mfma_f32_16x16x32_bf16 v[58:61], v[122:125], v[170:173], v[58:61]
	ds_read_b64 v[122:123], v224 offset:49408
	ds_read_b64 v[124:125], v225 offset:49408
	v_mfma_f32_16x16x32_bf16 v[62:65], v[126:129], v[170:173], v[62:65]
	ds_read_b64 v[126:127], v224 offset:57600
	ds_read_b64 v[128:129], v225 offset:57600
	s_waitcnt lgkmcnt(15)
; #define LAS __attribute__((address_space(3)))
; #define MFMA16(a, b, c) __builtin_amdgcn_mfma_f32_16x16x32_bf16((a), (b), (c), 0, 0, 0)
; DI void xattn_phase(LAS unsigned char* L, const bf16* Qx, const bf16* memK, const bf16* memVT, bf16* Ox, int G, int bid, int tid, unsigned long long& tsec) {
;     ...
; #pragma unroll
;             for (int pp = 0; pp < 8; ++pp)
; #pragma unroll
;                 for (int d4 = 0; d4 < 2; ++d4) { bf16x8 vf[4];
; #pragma unroll
;                     for (int dq = 0; dq < 4; ++dq) { const int dt = 4 * d4 + dq; const LAS unsigned char* vb_ = ((dt & 1) ? vod : vev) + 16 * dt * VSTR + 64 * pp;
;                         const s16x4 lo = *(const LAS s16x4*)(vb_ + (((2 * dt) & 4) << 3)), hi = *(const LAS s16x4*)(vb_ + ((((2 * dt) & 4) ^ 4) << 3)); vf[dq] = __builtin_shufflevector(lo, hi, 0, 1, 2, 3, 4, 5, 6, 7); }
; #pragma unroll
;                     for (int dq = 0; dq < 4; ++dq) o[4 * d4 + dq] = MFMA16(vf[dq], pf[pp], o[4 * d4 + dq]);
;                 }
	v_mfma_f32_16x16x32_bf16 v[34:37], v[130:133], v[174:177], v[34:37]
	ds_read_b64 v[130:131], v226 offset:256
	ds_read_b64 v[132:133], v227 offset:256
	v_mfma_f32_16x16x32_bf16 v[38:41], v[134:137], v[174:177], v[38:41]
	ds_read_b64 v[134:135], v226 offset:8448
	ds_read_b64 v[136:137], v227 offset:8448
	v_mfma_f32_16x16x32_bf16 v[42:45], v[138:141], v[174:177], v[42:45]
	ds_read_b64 v[138:139], v226 offset:16640
	ds_read_b64 v[140:141], v227 offset:16640
	v_mfma_f32_16x16x32_bf16 v[46:49], v[142:145], v[174:177], v[46:49]
	ds_read_b64 v[142:143], v226 offset:24832
	ds_read_b64 v[144:145], v227 offset:24832
	v_mfma_f32_16x16x32_bf16 v[50:53], v[146:149], v[174:177], v[50:53]
	ds_read_b64 v[146:147], v226 offset:33024
	ds_read_b64 v[148:149], v227 offset:33024
	v_mfma_f32_16x16x32_bf16 v[54:57], v[150:153], v[174:177], v[54:57]
	ds_read_b64 v[150:151], v226 offset:41216
	ds_read_b64 v[152:153], v227 offset:41216
	v_mfma_f32_16x16x32_bf16 v[58:61], v[154:157], v[174:177], v[58:61]
	ds_read_b64 v[154:155], v226 offset:49408
	ds_read_b64 v[156:157], v227 offset:49408
	v_mfma_f32_16x16x32_bf16 v[62:65], v[158:161], v[174:177], v[62:65]
	ds_read_b64 v[158:159], v226 offset:57600
	ds_read_b64 v[160:161], v227 offset:57600
	s_waitcnt lgkmcnt(15)
	v_mfma_f32_16x16x32_bf16 v[34:37], v[98:101], v[178:181], v[34:37]
	ds_read_b64 v[98:99], v228 offset:256
	ds_read_b64 v[100:101], v229 offset:256
	v_mfma_f32_16x16x32_bf16 v[38:41], v[102:105], v[178:181], v[38:41]
	ds_read_b64 v[102:103], v228 offset:8448
	ds_read_b64 v[104:105], v229 offset:8448
	v_mfma_f32_16x16x32_bf16 v[42:45], v[106:109], v[178:181], v[42:45]
	ds_read_b64 v[106:107], v228 offset:16640
	ds_read_b64 v[108:109], v229 offset:16640
	v_mfma_f32_16x16x32_bf16 v[46:49], v[110:113], v[178:181], v[46:49]
	ds_read_b64 v[110:111], v228 offset:24832
	ds_read_b64 v[112:113], v229 offset:24832
	v_mfma_f32_16x16x32_bf16 v[50:53], v[114:117], v[178:181], v[50:53]
	ds_read_b64 v[114:115], v228 offset:33024
	ds_read_b64 v[116:117], v229 offset:33024
	v_mfma_f32_16x16x32_bf16 v[54:57], v[118:121], v[178:181], v[54:57]
	ds_read_b64 v[118:119], v228 offset:41216
	ds_read_b64 v[120:121], v229 offset:41216
	v_mfma_f32_16x16x32_bf16 v[58:61], v[122:125], v[178:181], v[58:61]
	ds_read_b64 v[122:123], v228 offset:49408
	ds_read_b64 v[124:125], v229 offset:49408
	v_mfma_f32_16x16x32_bf16 v[62:65], v[126:129], v[178:181], v[62:65]
	ds_read_b64 v[126:127], v228 offset:57600
	ds_read_b64 v[128:129], v229 offset:57600
	s_waitcnt lgkmcnt(15)
	v_mfma_f32_16x16x32_bf16 v[34:37], v[130:133], v[182:185], v[34:37]
	ds_read_b64 v[130:131], v230 offset:256
	ds_read_b64 v[132:133], v231 offset:256
	v_mfma_f32_16x16x32_bf16 v[38:41], v[134:137], v[182:185], v[38:41]
	ds_read_b64 v[134:135], v230 offset:8448
	ds_read_b64 v[136:137], v231 offset:8448
	v_mfma_f32_16x16x32_bf16 v[42:45], v[138:141], v[182:185], v[42:45]
	ds_read_b64 v[138:139], v230 offset:16640
	ds_read_b64 v[140:141], v231 offset:16640
	v_mfma_f32_16x16x32_bf16 v[46:49], v[142:145], v[182:185], v[46:49]
	ds_read_b64 v[142:143], v230 offset:24832
	ds_read_b64 v[144:145], v231 offset:24832
	v_mfma_f32_16x16x32_bf16 v[50:53], v[146:149], v[182:185], v[50:53]
	ds_read_b64 v[146:147], v230 offset:33024
	ds_read_b64 v[148:149], v231 offset:33024
	v_mfma_f32_16x16x32_bf16 v[54:57], v[150:153], v[182:185], v[54:57]
	ds_read_b64 v[150:151], v230 offset:41216
	ds_read_b64 v[152:153], v231 offset:41216
	v_mfma_f32_16x16x32_bf16 v[58:61], v[154:157], v[182:185], v[58:61]
	ds_read_b64 v[154:155], v230 offset:49408
	ds_read_b64 v[156:157], v231 offset:49408
	v_mfma_f32_16x16x32_bf16 v[62:65], v[158:161], v[182:185], v[62:65]
	ds_read_b64 v[158:159], v230 offset:57600
	ds_read_b64 v[160:161], v231 offset:57600
	s_waitcnt lgkmcnt(15)
	v_mfma_f32_16x16x32_bf16 v[34:37], v[98:101], v[186:189], v[34:37]
	v_mfma_f32_16x16x32_bf16 v[38:41], v[102:105], v[186:189], v[38:41]
	v_mfma_f32_16x16x32_bf16 v[42:45], v[106:109], v[186:189], v[42:45]
	v_mfma_f32_16x16x32_bf16 v[46:49], v[110:113], v[186:189], v[46:49]
	v_mfma_f32_16x16x32_bf16 v[50:53], v[114:117], v[186:189], v[50:53]
	v_mfma_f32_16x16x32_bf16 v[54:57], v[118:121], v[186:189], v[54:57]
	v_mfma_f32_16x16x32_bf16 v[58:61], v[122:125], v[186:189], v[58:61]
	v_mfma_f32_16x16x32_bf16 v[62:65], v[126:129], v[186:189], v[62:65]
	s_waitcnt lgkmcnt(0)
; DI unsigned pk2(float lo, float hi) { const bf2_t r = __builtin_convertvector((f32x2_t){lo, hi}, bf2_t); return __builtin_bit_cast(unsigned, r); }
; #define MFMA16(a, b, c) __builtin_amdgcn_mfma_f32_16x16x32_bf16((a), (b), (c), 0, 0, 0)
; #define DSEC(k) do { if (PROBE_DSEC) { const unsigned long long tn_ = __builtin_amdgcn_s_memrealtime(); if (PROBE_DSEC == (k)) tsec += tn_ - tl_; tl_ = tn_; } } while (0)
; DI void xattn_phase(LAS unsigned char* L, const bf16* Qx, const bf16* memK, const bf16* memVT, bf16* Ox, int G, int bid, int tid, unsigned long long& tsec) {
;     ...
;                     for (int dq = 0; dq < 4; ++dq) o[4 * d4 + dq] = MFMA16(vf[dq], pf[pp], o[4 * d4 + dq]);
;                 }
;             { bf16* op = Ox + tq * D + h * 256 + 128 * hh + 4 * fq;
; #pragma unroll
;               for (int dt = 0; dt < 8; ++dt) *(unsigned long long*)(op + 16 * dt) = (unsigned long long)pk2(o[dt][0] * inv, o[dt][1] * inv) | ((unsigned long long)pk2(o[dt][2] * inv, o[dt][3] * inv) << 32); }
;         }
;         DSEC(14);
	v_mfma_f32_16x16x32_bf16 v[34:37], v[130:133], v[190:193], v[34:37]
	v_mfma_f32_16x16x32_bf16 v[38:41], v[134:137], v[190:193], v[38:41]
	v_mfma_f32_16x16x32_bf16 v[42:45], v[138:141], v[190:193], v[42:45]
	v_mfma_f32_16x16x32_bf16 v[46:49], v[142:145], v[190:193], v[46:49]
	v_mfma_f32_16x16x32_bf16 v[50:53], v[146:149], v[190:193], v[50:53]
	v_mfma_f32_16x16x32_bf16 v[54:57], v[150:153], v[190:193], v[54:57]
	v_mfma_f32_16x16x32_bf16 v[58:61], v[154:157], v[190:193], v[58:61]
	v_mfma_f32_16x16x32_bf16 v[62:65], v[158:161], v[190:193], v[62:65]
	v_mul_f32_e32 v2, v0, v2
	v_mul_f32_e32 v3, v0, v3
	v_mul_f32_e32 v4, v0, v4
	v_mul_f32_e32 v5, v0, v5
	v_cvt_pk_bf16_f32 v2, v2, v3
	v_cvt_pk_bf16_f32 v3, v4, v5
	global_store_dwordx2 v233, v[2:3], s[22:23]
	v_mul_f32_e32 v6, v0, v6
	v_mul_f32_e32 v7, v0, v7
	v_mul_f32_e32 v8, v0, v8
	v_mul_f32_e32 v9, v0, v9
	v_cvt_pk_bf16_f32 v6, v6, v7
	v_cvt_pk_bf16_f32 v7, v8, v9
	global_store_dwordx2 v233, v[6:7], s[22:23] offset:32
	v_mul_f32_e32 v10, v0, v10
	v_mul_f32_e32 v11, v0, v11
	v_mul_f32_e32 v12, v0, v12
	v_mul_f32_e32 v13, v0, v13
	v_cvt_pk_bf16_f32 v10, v10, v11
	v_cvt_pk_bf16_f32 v11, v12, v13
	global_store_dwordx2 v233, v[10:11], s[22:23] offset:64
	v_mul_f32_e32 v14, v0, v14
	v_mul_f32_e32 v15, v0, v15
	v_mul_f32_e32 v16, v0, v16
	v_mul_f32_e32 v17, v0, v17
	v_cvt_pk_bf16_f32 v14, v14, v15
	v_cvt_pk_bf16_f32 v15, v16, v17
	global_store_dwordx2 v233, v[14:15], s[22:23] offset:96
	v_mul_f32_e32 v18, v0, v18
	v_mul_f32_e32 v19, v0, v19
	v_mul_f32_e32 v20, v0, v20
	v_mul_f32_e32 v21, v0, v21
	v_cvt_pk_bf16_f32 v18, v18, v19
	v_cvt_pk_bf16_f32 v19, v20, v21
	global_store_dwordx2 v233, v[18:19], s[22:23] offset:128
	v_mul_f32_e32 v22, v0, v22
	v_mul_f32_e32 v23, v0, v23
	v_mul_f32_e32 v24, v0, v24
	v_mul_f32_e32 v25, v0, v25
	v_cvt_pk_bf16_f32 v22, v22, v23
	v_cvt_pk_bf16_f32 v23, v24, v25
	global_store_dwordx2 v233, v[22:23], s[22:23] offset:160
	v_mul_f32_e32 v26, v0, v26
	v_mul_f32_e32 v27, v0, v27
	v_mul_f32_e32 v28, v0, v28
	v_mul_f32_e32 v29, v0, v29
	v_cvt_pk_bf16_f32 v26, v26, v27
	v_cvt_pk_bf16_f32 v27, v28, v29
	global_store_dwordx2 v233, v[26:27], s[22:23] offset:192
	v_mul_f32_e32 v30, v0, v30
	v_mul_f32_e32 v31, v0, v31
	v_mul_f32_e32 v32, v0, v32
	v_mul_f32_e32 v33, v0, v33
	v_cvt_pk_bf16_f32 v30, v30, v31
	v_cvt_pk_bf16_f32 v31, v32, v33
	global_store_dwordx2 v233, v[30:31], s[22:23] offset:224
	v_mul_f32_e32 v34, v0, v34
	v_mul_f32_e32 v35, v0, v35
	v_mul_f32_e32 v36, v0, v36
	v_mul_f32_e32 v37, v0, v37
	v_cvt_pk_bf16_f32 v34, v34, v35
	v_cvt_pk_bf16_f32 v35, v36, v37
	global_store_dwordx2 v233, v[34:35], s[22:23] offset:256
	v_mul_f32_e32 v38, v0, v38
	v_mul_f32_e32 v39, v0, v39
	v_mul_f32_e32 v40, v0, v40
	v_mul_f32_e32 v41, v0, v41
	v_cvt_pk_bf16_f32 v38, v38, v39
	v_cvt_pk_bf16_f32 v39, v40, v41
	global_store_dwordx2 v233, v[38:39], s[22:23] offset:288
	v_mul_f32_e32 v42, v0, v42
	v_mul_f32_e32 v43, v0, v43
	v_mul_f32_e32 v44, v0, v44
	v_mul_f32_e32 v45, v0, v45
	v_cvt_pk_bf16_f32 v42, v42, v43
	v_cvt_pk_bf16_f32 v43, v44, v45
	global_store_dwordx2 v233, v[42:43], s[22:23] offset:320
	v_mul_f32_e32 v46, v0, v46
	v_mul_f32_e32 v47, v0, v47
	v_mul_f32_e32 v48, v0, v48
	v_mul_f32_e32 v49, v0, v49
	v_cvt_pk_bf16_f32 v46, v46, v47
	v_cvt_pk_bf16_f32 v47, v48, v49
	global_store_dwordx2 v233, v[46:47], s[22:23] offset:352
	v_mul_f32_e32 v50, v0, v50
	v_mul_f32_e32 v51, v0, v51
	v_mul_f32_e32 v52, v0, v52
	v_mul_f32_e32 v53, v0, v53
	v_cvt_pk_bf16_f32 v50, v50, v51
	v_cvt_pk_bf16_f32 v51, v52, v53
	global_store_dwordx2 v233, v[50:51], s[22:23] offset:384
	v_mul_f32_e32 v54, v0, v54
	v_mul_f32_e32 v55, v0, v55
	v_mul_f32_e32 v56, v0, v56
	v_mul_f32_e32 v57, v0, v57
	v_cvt_pk_bf16_f32 v54, v54, v55
	v_cvt_pk_bf16_f32 v55, v56, v57
	global_store_dwordx2 v233, v[54:55], s[22:23] offset:416
	v_mul_f32_e32 v58, v0, v58
	v_mul_f32_e32 v59, v0, v59
	v_mul_f32_e32 v60, v0, v60
	v_mul_f32_e32 v61, v0, v61
	v_cvt_pk_bf16_f32 v58, v58, v59
	v_cvt_pk_bf16_f32 v59, v60, v61
	global_store_dwordx2 v233, v[58:59], s[22:23] offset:448
	v_mul_f32_e32 v62, v0, v62
	v_mul_f32_e32 v63, v0, v63
	v_mul_f32_e32 v64, v0, v64
	v_mul_f32_e32 v65, v0, v65
	v_cvt_pk_bf16_f32 v62, v62, v63
	v_cvt_pk_bf16_f32 v63, v64, v65
	global_store_dwordx2 v233, v[62:63], s[22:23] offset:480
	s_setprio 0
